# FoX unit prologue: Q / first K-V tile / first forget-bias loads issued before the prefix-table build (serial round trips overlapped); on top of the SWA prologue and FoX loop wait fixes
# speedup vs baseline: 1.0107x; 1.0047x over previous
; template <int MODE> DI void attn_unit(int b, int qb, const bf16* Qb, int qpitch, const bf16* Kb, int kpitch, const bf16* VT, bf16* O, float* ssq, ...
;     ...
;     for (int d0 = 0; d0 < ND; ++d0) qr[d0] = *(const v8s*)(Qb + (rowbase + q) * qpitch + 16 * d0 + 8 * hi);
;     ...
;     ATT_LOAD(REV ? kt_hi : kt_lo); ATT_STORE(0);
.LBB0_481:
	s_xor_b64 s[20:21], s[22:23], -1
	s_and_b64 s[22:23], s[22:23], exec
	s_cselect_b32 s26, s58, s36
	s_lshl_b32 s59, s26, 8
	s_add_i32 s15, s59, s3
	v_or_b32_e32 v168, s15, v119
	v_mov_b32_e32 v169, v65
	v_lshl_add_u64 v[166:167], s[12:13], 0, v[168:169]
	v_lshlrev_b64 v[0:1], 12, v[166:167]
	v_lshl_add_u64 v[0:1], v[94:95], 0, v[0:1]
	global_load_dwordx4 v[66:69], v[0:1], off
	global_load_dwordx4 v[70:73], v[0:1], off offset:32
	global_load_dwordx4 v[74:77], v[0:1], off offset:64
	global_load_dwordx4 v[78:81], v[0:1], off offset:96
	s_or_b32 s27, s59, 0xc0
	s_or_b32 s22, s12, s27
	s_mov_b32 s23, s13
	v_lshl_add_u64 v[2:3], s[22:23], 0, v[122:123]
	v_lshlrev_b64 v[2:3], 12, v[2:3]
	v_lshl_add_u64 v[2:3], v[96:97], 0, v[2:3]
	s_lshl_b32 s72, s27, 1
	global_load_dwordx4 v[82:85], v[2:3], off
	v_lshl_add_u64 v[2:3], v[98:99], 0, s[72:73]
	global_load_dwordx4 v[86:89], v[2:3], off
	v_mov_b32_e32 v153, 0
	s_and_saveexec_b64 s[24:25], s[50:51]
	v_lshl_add_u64 v[2:3], s[22:23], 0, v[102:103]
	v_lshl_add_u64 v[2:3], v[2:3], 4, s[18:19]
	global_load_dword v251, v[2:3], off
	s_or_b64 exec, exec, s[24:25]
	s_cmp_lt_i32 s33, 1
	s_mov_b64 s[24:25], -1
	s_cbranch_scc1 .LBB0_489
	s_cmp_eq_u32 s33, 1
	s_cbranch_scc0 .LBB0_488
	v_mov_b32_e32 v0, 0
	s_and_saveexec_b64 s[24:25], s[56:57]
	s_cbranch_execz .LBB0_485
	global_load_dword v0, v[90:91], off

; DI float bf2f(unsigned short u) { return __uint_as_float((unsigned)u << 16); }
; template <int MODE> DI void attn_unit(int b, int qb, const bf16* Qb, int qpitch, const bf16* Kb, int kpitch, const bf16* VT, bf16* O, float* ssq, ...
;     ...
;     if (REV) {
; #pragma unroll
;         for (int d0 = 0; d0 < ND; ++d0)
; #pragma unroll
;             for (int j = 0; j < 8; ++j) { const float f = bf2f((unsigned short)qr[d0][j]); qn += f * f; }
;         qn += __shfl_xor(qn, 32); qn = sqrtf(qn) * 1.01f;
;     }
;     ATT_LOAD(REV ? kt_hi : kt_lo); ATT_STORE(0);
.LBB0_495:
	s_waitcnt lgkmcnt(0)
	s_barrier
	s_waitcnt vmcnt(5)
	v_and_b32_e32 v0, 0xffff0000, v66
	v_lshlrev_b32_e32 v1, 16, v66
	v_mul_f32_e32 v0, v0, v0
	v_fmac_f32_e32 v0, v1, v1
	v_lshlrev_b32_e32 v1, 16, v67
	v_fmac_f32_e32 v0, v1, v1
	v_and_b32_e32 v1, 0xffff0000, v67
	v_fmac_f32_e32 v0, v1, v1
	v_lshlrev_b32_e32 v1, 16, v68
	v_fmac_f32_e32 v0, v1, v1
	v_and_b32_e32 v1, 0xffff0000, v68
	v_fmac_f32_e32 v0, v1, v1
	v_lshlrev_b32_e32 v1, 16, v69
	v_fmac_f32_e32 v0, v1, v1
	v_and_b32_e32 v1, 0xffff0000, v69
	v_fmac_f32_e32 v0, v1, v1
	s_waitcnt vmcnt(4)
	v_lshlrev_b32_e32 v1, 16, v70
	v_fmac_f32_e32 v0, v1, v1
	v_and_b32_e32 v1, 0xffff0000, v70
	v_fmac_f32_e32 v0, v1, v1
	v_lshlrev_b32_e32 v1, 16, v71
	v_fmac_f32_e32 v0, v1, v1
	v_and_b32_e32 v1, 0xffff0000, v71
	v_fmac_f32_e32 v0, v1, v1
	v_lshlrev_b32_e32 v1, 16, v72
	v_fmac_f32_e32 v0, v1, v1
	v_and_b32_e32 v1, 0xffff0000, v72
	v_fmac_f32_e32 v0, v1, v1
	v_lshlrev_b32_e32 v1, 16, v73
	v_fmac_f32_e32 v0, v1, v1
	v_and_b32_e32 v1, 0xffff0000, v73
	v_fmac_f32_e32 v0, v1, v1
	s_waitcnt vmcnt(3)
	v_lshlrev_b32_e32 v1, 16, v74
	v_fmac_f32_e32 v0, v1, v1
	v_and_b32_e32 v1, 0xffff0000, v74
	v_fmac_f32_e32 v0, v1, v1
	v_lshlrev_b32_e32 v1, 16, v75
	v_fmac_f32_e32 v0, v1, v1
	v_and_b32_e32 v1, 0xffff0000, v75
	v_fmac_f32_e32 v0, v1, v1
	v_lshlrev_b32_e32 v1, 16, v76
	v_fmac_f32_e32 v0, v1, v1
	v_and_b32_e32 v1, 0xffff0000, v76
	v_fmac_f32_e32 v0, v1, v1
	v_lshlrev_b32_e32 v1, 16, v77
	v_fmac_f32_e32 v0, v1, v1
	v_and_b32_e32 v1, 0xffff0000, v77
	v_fmac_f32_e32 v0, v1, v1
	s_waitcnt vmcnt(2)
	v_lshlrev_b32_e32 v1, 16, v78
	v_fmac_f32_e32 v0, v1, v1
	v_and_b32_e32 v1, 0xffff0000, v78
	v_fmac_f32_e32 v0, v1, v1
	v_lshlrev_b32_e32 v1, 16, v79
	v_fmac_f32_e32 v0, v1, v1
	v_and_b32_e32 v1, 0xffff0000, v79
	v_fmac_f32_e32 v0, v1, v1
	v_lshlrev_b32_e32 v1, 16, v80
	v_fmac_f32_e32 v0, v1, v1
	v_and_b32_e32 v1, 0xffff0000, v80
	v_fmac_f32_e32 v0, v1, v1
	v_lshlrev_b32_e32 v1, 16, v81
	v_fmac_f32_e32 v0, v1, v1
	v_and_b32_e32 v1, 0xffff0000, v81
	v_fmac_f32_e32 v0, v1, v1
	ds_bpermute_b32 v1, v190, v0
	s_and_saveexec_b64 s[24:25], s[50:51]
	s_cbranch_execz .LBB0_497
	v_add_u32_e32 v3, s27, v102
	v_ashrrev_i32_e32 v3, 7, v3
	v_lshl_add_u32 v3, v3, 2, 0
	ds_read_b32 v3, v3 offset:36352
	s_waitcnt vmcnt(0) lgkmcnt(0)
	v_add_f32_e32 v2, v251, v3
	v_mul_f32_e32 v153, 0xbfb8aa3b, v2
